# lru_prompt pass 1: the 16 loads of a chunk issued together (was ~7 wait rounds per 8 tokens); delta_seq: B-operand reads overlapped with the A-read wait, two-stream output epilogue
# speedup vs baseline: 1.0156x; 1.0018x over previous
.LBB0_710:
	v_add_co_u32_e32 v4, vcc, 0xff770000, v0
	global_load_ushort v10, v[0:1], off offset:-3584
	s_nop 0
	v_addc_co_u32_e32 v5, vcc, -1, v1, vcc
	global_load_ushort v8, v[4:5], off offset:-3584
	global_load_ushort v102, v[0:1], off offset:-2560
	global_load_ushort v103, v[4:5], off offset:-2560
	global_load_ushort v104, v[0:1], off offset:-3072
	global_load_ushort v105, v[0:1], off offset:-2048
	global_load_ushort v106, v[4:5], off offset:-1536
	global_load_ushort v107, v[4:5], off offset:-512
	global_load_ushort v108, v[4:5], off offset:-3072
	global_load_ushort v109, v[0:1], off offset:-1536
	global_load_ushort v110, v[4:5], off offset:-2048
	global_load_ushort v111, v[0:1], off offset:-1024
	global_load_ushort v112, v[4:5], off offset:-1024
	global_load_ushort v113, v[0:1], off offset:-512
	global_load_ushort v114, v[4:5], off
	global_load_ushort v115, v[0:1], off
	s_add_i32 s11, s11, 8
	s_cmp_lt_i32 s11, s14
	s_waitcnt vmcnt(15)
	v_lshlrev_b32_e32 v13, 16, v10
	s_waitcnt vmcnt(13)
	v_mov_b32_e32 v10, v102
	s_waitcnt vmcnt(14)
	v_lshlrev_b32_e32 v8, 16, v8
	v_mul_f32_e32 v9, 0x3fb8aa3b, v8
	v_exp_f32_e32 v9, v9
	v_add_f32_e32 v2, v2, v8
	s_waitcnt vmcnt(12)
	v_mov_b32_e32 v8, v103
	v_fmac_f32_e32 v13, v3, v9
	s_waitcnt vmcnt(11)
	v_mov_b32_e32 v3, v104
	v_lshlrev_b32_e32 v18, 16, v10
	s_waitcnt vmcnt(10)
	v_mov_b32_e32 v10, v105
	v_lshlrev_b32_e32 v8, 16, v8
	v_mul_f32_e32 v9, 0x3fb8aa3b, v8
	v_exp_f32_e32 v9, v9
	v_lshlrev_b32_e32 v3, 16, v3
	v_lshlrev_b32_e32 v19, 16, v10
	s_waitcnt vmcnt(9)
	v_mov_b32_e32 v10, v106
	v_lshlrev_b32_e32 v10, 16, v10
	v_mul_f32_e32 v11, 0x3fb8aa3b, v10
	v_exp_f32_e32 v20, v11
	s_waitcnt vmcnt(8)
	v_mov_b32_e32 v11, v107
	s_waitcnt vmcnt(7)
	v_mov_b32_e32 v14, v108
	s_waitcnt vmcnt(6)
	v_mov_b32_e32 v15, v109
	v_lshlrev_b32_e32 v14, 16, v14
	v_mul_f32_e32 v16, 0x3fb8aa3b, v14
	v_lshlrev_b32_e32 v15, 16, v15
	v_exp_f32_e32 v16, v16
	v_lshlrev_b32_e32 v12, 16, v11
	v_mul_f32_e32 v11, 0x3fb8aa3b, v12
	v_exp_f32_e32 v11, v11
	v_fmac_f32_e32 v3, v13, v16
	v_fmac_f32_e32 v18, v3, v9
	s_waitcnt vmcnt(5)
	v_mov_b32_e32 v3, v110
	s_waitcnt vmcnt(4)
	v_mov_b32_e32 v9, v111
	v_lshlrev_b32_e32 v16, 16, v3
	v_lshlrev_b32_e32 v17, 16, v9
	s_waitcnt vmcnt(3)
	v_mov_b32_e32 v9, v112
	s_waitcnt vmcnt(2)
	v_mov_b32_e32 v13, v113
	s_nop 0
	s_waitcnt vmcnt(1)
	v_mov_b32_e32 v4, v114
	s_nop 0
	s_waitcnt vmcnt(0)
	v_mov_b32_e32 v5, v115
	v_mul_f32_e32 v3, 0x3fb8aa3b, v16
	v_exp_f32_e32 v3, v3
	v_lshl_add_u64 v[0:1], v[0:1], 0, s[16:17]
	v_fmac_f32_e32 v19, v18, v3
	v_mul_f32_e32 v3, v19, v20
	v_pk_add_f32 v[2:3], v[2:3], v[14:15]
	v_lshlrev_b32_e32 v14, 16, v9
	v_mul_f32_e32 v9, 0x3fb8aa3b, v14
	v_exp_f32_e32 v9, v9
	v_lshlrev_b32_e32 v15, 16, v13
	v_lshlrev_b32_e32 v4, 16, v4
	v_lshlrev_b32_e32 v5, 16, v5
	v_pk_add_f32 v[18:19], v[2:3], v[8:9]
	v_pk_mul_f32 v[2:3], v[2:3], v[8:9]
	s_nop 0
	v_mov_b32_e32 v19, v3
	v_pk_add_f32 v[2:3], v[18:19], v[16:17]
	s_nop 0
	v_pk_add_f32 v[8:9], v[2:3], v[10:11]
	v_pk_mul_f32 v[2:3], v[2:3], v[10:11]
	s_nop 0
	v_mov_b32_e32 v9, v3
	v_pk_add_f32 v[2:3], v[8:9], v[14:15]
	v_mul_f32_e32 v8, 0x3fb8aa3b, v4
	v_exp_f32_e32 v13, v8
	s_nop 0
	v_pk_add_f32 v[8:9], v[2:3], v[12:13]
	v_pk_mul_f32 v[2:3], v[2:3], v[12:13]
	s_nop 0
	v_mov_b32_e32 v9, v3
	v_pk_add_f32 v[2:3], v[8:9], v[4:5]
	s_cbranch_scc1 .LBB0_710
